# as v2 plus P4 and P10 loop fragment register alignment
# speedup vs baseline: 1.0075x; 1.0075x over previous
.LBB0_649:
	ds_read_b128 v[224:227], v161
	ds_read_b128 v[146:149], v161 offset:1024
	ds_read_b128 v[220:223], v161 offset:2048
	ds_read_b128 v[150:153], v161 offset:3072
	ds_read_b128 v[216:219], v162
	ds_read_b128 v[166:169], v162 offset:1024
	ds_read_b128 v[212:215], v162 offset:2048
	ds_read_b128 v[170:173], v162 offset:3072
	s_add_u32 s8, s4, 0xfff00080
	s_addc_u32 s9, s5, -1
	s_cmp_eq_u32 s57, 60
	s_cselect_b32 s53, s1, s9
	s_cselect_b32 s52, s7, s8
	s_cselect_b32 s9, s11, s55
	s_cselect_b32 s8, s12, s33
	v_lshl_add_u64 v[154:155], s[4:5], 0, v[142:143]
	s_add_i32 m0, s64, 0xc000
	ds_read_b128 v[174:177], v163
	ds_read_b128 v[178:181], v163 offset:1024
	ds_read_b128 v[182:185], v163 offset:2048
	ds_read_b128 v[186:189], v163 offset:3072
	ds_read_b128 v[190:193], v163 offset:4096
	ds_read_b128 v[194:197], v163 offset:5120
	ds_read_b128 v[198:201], v163 offset:6144
	ds_read_b128 v[206:209], v163 offset:7168
	global_load_lds_dwordx4 v[154:155], off
	v_lshl_add_u64 v[154:155], s[4:5], 0, v[144:145]
	s_add_i32 m0, s64, 0xe000
	s_nop 0
	global_load_lds_dwordx4 v[154:155], off
	s_waitcnt vmcnt(8)
	s_waitcnt lgkmcnt(0)
	s_barrier
	s_setprio 1
	s_waitcnt lgkmcnt(0)
	v_mfma_f32_16x16x32_bf16 v[126:129], v[224:227], v[174:177], v[126:129]
	v_mfma_f32_16x16x32_bf16 v[126:129], v[146:149], v[178:181], v[126:129]
	v_mfma_f32_16x16x32_bf16 v[122:125], v[220:223], v[174:177], v[122:125]
	v_mfma_f32_16x16x32_bf16 v[122:125], v[150:153], v[178:181], v[122:125]
	v_mfma_f32_16x16x32_bf16 v[106:109], v[220:223], v[182:185], v[106:109]
	v_mfma_f32_16x16x32_bf16 v[106:109], v[150:153], v[186:189], v[106:109]
	v_mfma_f32_16x16x32_bf16 v[110:113], v[224:227], v[182:185], v[110:113]
	v_mfma_f32_16x16x32_bf16 v[110:113], v[146:149], v[186:189], v[110:113]
	v_mfma_f32_16x16x32_bf16 v[94:97], v[224:227], v[190:193], v[94:97]
	v_mfma_f32_16x16x32_bf16 v[94:97], v[146:149], v[194:197], v[94:97]
	v_mfma_f32_16x16x32_bf16 v[90:93], v[220:223], v[190:193], v[90:93]
	v_mfma_f32_16x16x32_bf16 v[90:93], v[150:153], v[194:197], v[90:93]
	v_mfma_f32_16x16x32_bf16 v[74:77], v[220:223], v[198:201], v[74:77]
	v_mfma_f32_16x16x32_bf16 v[74:77], v[150:153], v[206:209], v[74:77]
	v_mfma_f32_16x16x32_bf16 v[78:81], v[224:227], v[198:201], v[78:81]
	v_mfma_f32_16x16x32_bf16 v[78:81], v[146:149], v[206:209], v[78:81]
	s_setprio 0
	s_setprio 1
	v_mfma_f32_16x16x32_bf16 v[118:121], v[216:219], v[174:177], v[118:121]
	v_mfma_f32_16x16x32_bf16 v[118:121], v[166:169], v[178:181], v[118:121]
	v_mfma_f32_16x16x32_bf16 v[114:117], v[212:215], v[174:177], v[114:117]
	v_mfma_f32_16x16x32_bf16 v[114:117], v[170:173], v[178:181], v[114:117]
	v_mfma_f32_16x16x32_bf16 v[98:101], v[212:215], v[182:185], v[98:101]
	v_mfma_f32_16x16x32_bf16 v[98:101], v[170:173], v[186:189], v[98:101]
	v_mfma_f32_16x16x32_bf16 v[102:105], v[216:219], v[182:185], v[102:105]
	v_mfma_f32_16x16x32_bf16 v[102:105], v[166:169], v[186:189], v[102:105]
	v_mfma_f32_16x16x32_bf16 v[86:89], v[216:219], v[190:193], v[86:89]
	v_mfma_f32_16x16x32_bf16 v[86:89], v[166:169], v[194:197], v[86:89]
	v_mfma_f32_16x16x32_bf16 v[82:85], v[212:215], v[190:193], v[82:85]
	v_mfma_f32_16x16x32_bf16 v[82:85], v[170:173], v[194:197], v[82:85]
	v_mfma_f32_16x16x32_bf16 v[66:69], v[212:215], v[198:201], v[66:69]
	v_mfma_f32_16x16x32_bf16 v[66:69], v[170:173], v[206:209], v[66:69]
	v_mfma_f32_16x16x32_bf16 v[70:73], v[216:219], v[198:201], v[70:73]
	v_mfma_f32_16x16x32_bf16 v[70:73], v[166:169], v[206:209], v[70:73]
	s_setprio 0
	s_barrier
	s_add_i32 s26, s86, s59
	v_lshl_add_u64 v[154:155], s[8:9], 0, v[132:133]
	s_mov_b32 m0, s26
	ds_read_b128 v[174:177], v163 offset:16384
	ds_read_b128 v[178:181], v163 offset:17408
	ds_read_b128 v[182:185], v163 offset:18432
	ds_read_b128 v[186:189], v163 offset:19456
	ds_read_b128 v[190:193], v163 offset:20480
	ds_read_b128 v[194:197], v163 offset:21504
	ds_read_b128 v[198:201], v163 offset:22528
	ds_read_b128 v[206:209], v163 offset:23552
	global_load_lds_dwordx4 v[154:155], off
	s_add_i32 m0, s26, 0x2000
	s_add_u32 s26, s8, 0x100000
	v_lshl_add_u64 v[164:165], s[8:9], 0, v[136:137]
	s_addc_u32 s27, s9, 0
	s_add_i32 s28, s87, s59
	global_load_lds_dwordx4 v[164:165], off
	v_lshl_add_u64 v[202:203], s[26:27], 0, v[132:133]
	s_mov_b32 m0, s28
	v_lshl_add_u64 v[210:211], s[52:53], 0, v[134:135]
	global_load_lds_dwordx4 v[202:203], off
	v_lshl_add_u64 v[202:203], s[26:27], 0, v[136:137]
	s_add_i32 m0, s28, 0x2000
	s_nop 0
	global_load_lds_dwordx4 v[202:203], off
	v_lshl_add_u64 v[202:203], s[52:53], 0, v[130:131]
	s_mov_b32 m0, s64
	s_nop 0
	global_load_lds_dwordx4 v[202:203], off
	s_mov_b32 m0, s65
	s_nop 0
	global_load_lds_dwordx4 v[210:211], off
	s_waitcnt vmcnt(8)
	s_waitcnt lgkmcnt(0)
	s_barrier
	s_setprio 1
	s_waitcnt lgkmcnt(0)
	v_mfma_f32_16x16x32_bf16 v[62:65], v[224:227], v[174:177], v[62:65]
	v_mfma_f32_16x16x32_bf16 v[62:65], v[146:149], v[178:181], v[62:65]
	v_mfma_f32_16x16x32_bf16 v[58:61], v[220:223], v[174:177], v[58:61]
	v_mfma_f32_16x16x32_bf16 v[58:61], v[150:153], v[178:181], v[58:61]
	v_mfma_f32_16x16x32_bf16 v[42:45], v[220:223], v[182:185], v[42:45]
	v_mfma_f32_16x16x32_bf16 v[42:45], v[150:153], v[186:189], v[42:45]
	v_mfma_f32_16x16x32_bf16 v[46:49], v[224:227], v[182:185], v[46:49]
	v_mfma_f32_16x16x32_bf16 v[46:49], v[146:149], v[186:189], v[46:49]
	v_mfma_f32_16x16x32_bf16 v[30:33], v[224:227], v[190:193], v[30:33]
	v_mfma_f32_16x16x32_bf16 v[30:33], v[146:149], v[194:197], v[30:33]
	v_mfma_f32_16x16x32_bf16 v[26:29], v[220:223], v[190:193], v[26:29]
	v_mfma_f32_16x16x32_bf16 v[26:29], v[150:153], v[194:197], v[26:29]
	v_mfma_f32_16x16x32_bf16 v[10:13], v[220:223], v[198:201], v[10:13]
	v_mfma_f32_16x16x32_bf16 v[10:13], v[150:153], v[206:209], v[10:13]
	v_mfma_f32_16x16x32_bf16 v[14:17], v[224:227], v[198:201], v[14:17]
	v_mfma_f32_16x16x32_bf16 v[14:17], v[146:149], v[206:209], v[14:17]
	s_setprio 0
	s_setprio 1
	v_mfma_f32_16x16x32_bf16 v[54:57], v[216:219], v[174:177], v[54:57]
	v_mfma_f32_16x16x32_bf16 v[54:57], v[166:169], v[178:181], v[54:57]
	v_mfma_f32_16x16x32_bf16 v[50:53], v[212:215], v[174:177], v[50:53]
	v_mfma_f32_16x16x32_bf16 v[50:53], v[170:173], v[178:181], v[50:53]
	v_mfma_f32_16x16x32_bf16 v[34:37], v[212:215], v[182:185], v[34:37]
	v_mfma_f32_16x16x32_bf16 v[34:37], v[170:173], v[186:189], v[34:37]
	v_mfma_f32_16x16x32_bf16 v[38:41], v[216:219], v[182:185], v[38:41]
	v_mfma_f32_16x16x32_bf16 v[38:41], v[166:169], v[186:189], v[38:41]
	v_mfma_f32_16x16x32_bf16 v[22:25], v[216:219], v[190:193], v[22:25]
	v_mfma_f32_16x16x32_bf16 v[22:25], v[166:169], v[194:197], v[22:25]
	v_mfma_f32_16x16x32_bf16 v[18:21], v[212:215], v[190:193], v[18:21]
	v_mfma_f32_16x16x32_bf16 v[18:21], v[170:173], v[194:197], v[18:21]
	v_mfma_f32_16x16x32_bf16 v[2:5], v[212:215], v[198:201], v[2:5]
	v_mfma_f32_16x16x32_bf16 v[2:5], v[170:173], v[206:209], v[2:5]
	v_mfma_f32_16x16x32_bf16 v[6:9], v[216:219], v[198:201], v[6:9]
	v_mfma_f32_16x16x32_bf16 v[6:9], v[166:169], v[206:209], v[6:9]
	s_setprio 0
	s_barrier
	s_add_i32 s28, 0, 0x18000
	v_add_u32_e32 v140, s28, v156
	s_add_i32 s29, 0, 0x1c000
	ds_read_b128 v[224:227], v140
	ds_read_b128 v[146:149], v140 offset:1024
	ds_read_b128 v[220:223], v140 offset:2048
	ds_read_b128 v[150:153], v140 offset:3072
	v_add_u32_e32 v140, s29, v156
	ds_read_b128 v[216:219], v140
	ds_read_b128 v[166:169], v140 offset:1024
	ds_read_b128 v[212:215], v140 offset:2048
	ds_read_b128 v[170:173], v140 offset:3072
	s_add_u32 s26, s52, 0x100000
	s_addc_u32 s27, s53, 0
	s_mov_b32 m0, s66
	v_lshl_add_u64 v[228:229], s[26:27], 0, v[130:131]
	ds_read_b128 v[174:177], v163 offset:32768
	ds_read_b128 v[178:181], v163 offset:33792
	ds_read_b128 v[182:185], v163 offset:34816
	ds_read_b128 v[186:189], v163 offset:35840
	ds_read_b128 v[190:193], v163 offset:36864
	ds_read_b128 v[194:197], v163 offset:37888
	ds_read_b128 v[198:201], v163 offset:38912
	ds_read_b128 v[206:209], v163 offset:39936
	global_load_lds_dwordx4 v[228:229], off
	v_lshl_add_u64 v[228:229], s[26:27], 0, v[134:135]
	s_mov_b32 m0, s67
	s_nop 0
	global_load_lds_dwordx4 v[228:229], off
	s_waitcnt vmcnt(8)
	s_waitcnt lgkmcnt(0)
	s_barrier
	s_setprio 1
	s_waitcnt lgkmcnt(0)
	v_mfma_f32_16x16x32_bf16 v[126:129], v[224:227], v[174:177], v[126:129]
	v_mfma_f32_16x16x32_bf16 v[126:129], v[146:149], v[178:181], v[126:129]
	v_mfma_f32_16x16x32_bf16 v[122:125], v[220:223], v[174:177], v[122:125]
	v_mfma_f32_16x16x32_bf16 v[122:125], v[150:153], v[178:181], v[122:125]
	v_mfma_f32_16x16x32_bf16 v[106:109], v[220:223], v[182:185], v[106:109]
	v_mfma_f32_16x16x32_bf16 v[106:109], v[150:153], v[186:189], v[106:109]
	v_mfma_f32_16x16x32_bf16 v[110:113], v[224:227], v[182:185], v[110:113]
	v_mfma_f32_16x16x32_bf16 v[110:113], v[146:149], v[186:189], v[110:113]
	v_mfma_f32_16x16x32_bf16 v[94:97], v[224:227], v[190:193], v[94:97]
	v_mfma_f32_16x16x32_bf16 v[94:97], v[146:149], v[194:197], v[94:97]
	v_mfma_f32_16x16x32_bf16 v[90:93], v[220:223], v[190:193], v[90:93]
	v_mfma_f32_16x16x32_bf16 v[90:93], v[150:153], v[194:197], v[90:93]
	v_mfma_f32_16x16x32_bf16 v[74:77], v[220:223], v[198:201], v[74:77]
	v_mfma_f32_16x16x32_bf16 v[74:77], v[150:153], v[206:209], v[74:77]
	v_mfma_f32_16x16x32_bf16 v[78:81], v[224:227], v[198:201], v[78:81]
	v_mfma_f32_16x16x32_bf16 v[78:81], v[146:149], v[206:209], v[78:81]
	s_setprio 0
	s_setprio 1
	v_mfma_f32_16x16x32_bf16 v[118:121], v[216:219], v[174:177], v[118:121]
	v_mfma_f32_16x16x32_bf16 v[118:121], v[166:169], v[178:181], v[118:121]
	v_mfma_f32_16x16x32_bf16 v[114:117], v[212:215], v[174:177], v[114:117]
	v_mfma_f32_16x16x32_bf16 v[114:117], v[170:173], v[178:181], v[114:117]
	v_mfma_f32_16x16x32_bf16 v[98:101], v[212:215], v[182:185], v[98:101]
	v_mfma_f32_16x16x32_bf16 v[98:101], v[170:173], v[186:189], v[98:101]
	v_mfma_f32_16x16x32_bf16 v[102:105], v[216:219], v[182:185], v[102:105]
	v_mfma_f32_16x16x32_bf16 v[102:105], v[166:169], v[186:189], v[102:105]
	v_mfma_f32_16x16x32_bf16 v[86:89], v[216:219], v[190:193], v[86:89]
	v_mfma_f32_16x16x32_bf16 v[86:89], v[166:169], v[194:197], v[86:89]
	v_mfma_f32_16x16x32_bf16 v[82:85], v[212:215], v[190:193], v[82:85]
	v_mfma_f32_16x16x32_bf16 v[82:85], v[170:173], v[194:197], v[82:85]
	v_mfma_f32_16x16x32_bf16 v[66:69], v[212:215], v[198:201], v[66:69]
	v_mfma_f32_16x16x32_bf16 v[66:69], v[170:173], v[206:209], v[66:69]
	v_mfma_f32_16x16x32_bf16 v[70:73], v[216:219], v[198:201], v[70:73]
	v_mfma_f32_16x16x32_bf16 v[70:73], v[166:169], v[206:209], v[70:73]
	s_setprio 0
	s_barrier
	s_add_i32 s26, s28, s59
	v_lshl_add_u64 v[154:155], v[154:155], 0, s[38:39]
	s_mov_b32 m0, s26
	ds_read_b128 v[174:177], v163 offset:49152
	ds_read_b128 v[178:181], v163 offset:50176
	ds_read_b128 v[182:185], v163 offset:51200
	ds_read_b128 v[186:189], v163 offset:52224
	ds_read_b128 v[190:193], v163 offset:53248
	ds_read_b128 v[194:197], v163 offset:54272
	ds_read_b128 v[198:201], v163 offset:55296
	ds_read_b128 v[206:209], v163 offset:56320
	global_load_lds_dwordx4 v[154:155], off
	s_add_i32 m0, s26, 0x2000
	s_add_u32 s8, s8, 0x100080
	v_lshl_add_u64 v[154:155], v[164:165], 0, s[38:39]
	s_addc_u32 s9, s9, 0
	s_add_i32 s26, s29, s59
	global_load_lds_dwordx4 v[154:155], off
	v_lshl_add_u64 v[154:155], s[8:9], 0, v[132:133]
	s_mov_b32 m0, s26
	s_nop 0
	global_load_lds_dwordx4 v[154:155], off
	v_lshl_add_u64 v[154:155], s[8:9], 0, v[136:137]
	s_add_i32 m0, s26, 0x2000
	s_nop 0
	global_load_lds_dwordx4 v[154:155], off
	v_lshl_add_u64 v[154:155], v[202:203], 0, s[38:39]
	s_mov_b32 m0, s22
	s_nop 0
	global_load_lds_dwordx4 v[154:155], off
	v_lshl_add_u64 v[154:155], v[210:211], 0, s[38:39]
	s_mov_b32 m0, s23
	s_nop 0
	global_load_lds_dwordx4 v[154:155], off
	s_waitcnt vmcnt(8)
	s_waitcnt lgkmcnt(0)
	s_barrier
	s_setprio 1
	s_waitcnt lgkmcnt(0)
	v_mfma_f32_16x16x32_bf16 v[62:65], v[224:227], v[174:177], v[62:65]
	v_mfma_f32_16x16x32_bf16 v[62:65], v[146:149], v[178:181], v[62:65]
	v_mfma_f32_16x16x32_bf16 v[58:61], v[220:223], v[174:177], v[58:61]
	v_mfma_f32_16x16x32_bf16 v[58:61], v[150:153], v[178:181], v[58:61]
	v_mfma_f32_16x16x32_bf16 v[42:45], v[220:223], v[182:185], v[42:45]
	v_mfma_f32_16x16x32_bf16 v[42:45], v[150:153], v[186:189], v[42:45]
	v_mfma_f32_16x16x32_bf16 v[46:49], v[224:227], v[182:185], v[46:49]
	v_mfma_f32_16x16x32_bf16 v[46:49], v[146:149], v[186:189], v[46:49]
	v_mfma_f32_16x16x32_bf16 v[30:33], v[224:227], v[190:193], v[30:33]
	v_mfma_f32_16x16x32_bf16 v[30:33], v[146:149], v[194:197], v[30:33]
	v_mfma_f32_16x16x32_bf16 v[26:29], v[220:223], v[190:193], v[26:29]
	v_mfma_f32_16x16x32_bf16 v[26:29], v[150:153], v[194:197], v[26:29]
	v_mfma_f32_16x16x32_bf16 v[10:13], v[220:223], v[198:201], v[10:13]
	v_mfma_f32_16x16x32_bf16 v[10:13], v[150:153], v[206:209], v[10:13]
	v_mfma_f32_16x16x32_bf16 v[14:17], v[224:227], v[198:201], v[14:17]
	v_mfma_f32_16x16x32_bf16 v[14:17], v[146:149], v[206:209], v[14:17]
	s_setprio 0
	s_setprio 1
	v_mfma_f32_16x16x32_bf16 v[54:57], v[216:219], v[174:177], v[54:57]
	v_mfma_f32_16x16x32_bf16 v[54:57], v[166:169], v[178:181], v[54:57]
	v_mfma_f32_16x16x32_bf16 v[50:53], v[212:215], v[174:177], v[50:53]
	v_mfma_f32_16x16x32_bf16 v[50:53], v[170:173], v[178:181], v[50:53]
	v_mfma_f32_16x16x32_bf16 v[34:37], v[212:215], v[182:185], v[34:37]
	v_mfma_f32_16x16x32_bf16 v[34:37], v[170:173], v[186:189], v[34:37]
	v_mfma_f32_16x16x32_bf16 v[38:41], v[216:219], v[182:185], v[38:41]
	v_mfma_f32_16x16x32_bf16 v[38:41], v[166:169], v[186:189], v[38:41]
	v_mfma_f32_16x16x32_bf16 v[22:25], v[216:219], v[190:193], v[22:25]
	v_mfma_f32_16x16x32_bf16 v[22:25], v[166:169], v[194:197], v[22:25]
	v_mfma_f32_16x16x32_bf16 v[18:21], v[212:215], v[190:193], v[18:21]
	v_mfma_f32_16x16x32_bf16 v[18:21], v[170:173], v[194:197], v[18:21]
	v_mfma_f32_16x16x32_bf16 v[2:5], v[212:215], v[198:201], v[2:5]
	v_mfma_f32_16x16x32_bf16 v[2:5], v[170:173], v[206:209], v[2:5]
	v_mfma_f32_16x16x32_bf16 v[6:9], v[216:219], v[198:201], v[6:9]
	v_mfma_f32_16x16x32_bf16 v[6:9], v[166:169], v[206:209], v[6:9]
	s_setprio 0
	s_barrier
	s_add_i32 s57, s57, 2
	s_add_u32 s4, s4, 0x100
	s_addc_u32 s5, s5, 0
	s_add_u32 s33, s33, 0x100
	s_addc_u32 s55, s55, 0
	s_cmp_gt_u32 s57, 61
	s_cbranch_scc0 .LBB0_649
	s_and_b64 vcc, exec, s[40:41]
	s_cbranch_vccz .LBB0_652
	s_barrier

.LBB0_1283:
	s_add_i32 s14, s54, s58
	s_cmp_lg_u32 s58, 0
	s_cselect_b64 s[60:61], -1, 0
	s_and_b32 s59, s14, 0xffffffef
	s_cmp_eq_u32 s59, 32
	s_cselect_b64 vcc, -1, 0
	s_and_b64 s[60:61], s[60:61], vcc
	s_andn2_b64 vcc, exec, s[60:61]
	s_cbranch_vccnz .LBB0_1285
	s_cmp_eq_u32 s14, 32
	s_cselect_b32 s14, 0, 0x1000
	v_lshl_add_u64 v[4:5], v[174:175], 0, s[14:15]
	v_lshl_add_u64 v[248:249], v[4:5], 0, v[158:159]
	v_add_co_u32_e32 v250, vcc, 0x1000, v248
	global_load_dwordx2 v[190:191], v[248:249], off
	s_nop 0
	v_addc_co_u32_e32 v251, vcc, 0, v249, vcc
	global_load_dwordx2 v[192:193], v[250:251], off
	global_load_dwordx2 v[236:237], v[248:249], off offset:128
	global_load_dwordx2 v[238:239], v[250:251], off offset:128
	v_lshl_add_u64 v[248:249], v[4:5], 0, v[160:161]
	v_add_co_u32_e32 v250, vcc, 0x1000, v248
	global_load_dwordx2 v[186:187], v[248:249], off
	s_nop 0
	v_addc_co_u32_e32 v251, vcc, 0, v249, vcc
	global_load_dwordx2 v[188:189], v[250:251], off
	global_load_dwordx2 v[184:185], v[248:249], off offset:128
	global_load_dwordx2 v[242:243], v[250:251], off offset:128
	v_lshl_add_u64 v[248:249], v[4:5], 0, v[162:163]
	v_add_co_u32_e32 v250, vcc, 0x1000, v248
	global_load_dwordx2 v[182:183], v[248:249], off
	s_nop 0
	v_addc_co_u32_e32 v251, vcc, 0, v249, vcc
	global_load_dwordx2 v[240:241], v[250:251], off
	global_load_dwordx2 v[178:179], v[248:249], off offset:128
	global_load_dwordx2 v[246:247], v[250:251], off offset:128
	v_lshl_add_u64 v[248:249], v[4:5], 0, v[164:165]
	v_add_co_u32_e32 v244, vcc, 0x1000, v248
	global_load_dwordx2 v[250:251], v[248:249], off
	s_nop 0
	v_addc_co_u32_e32 v245, vcc, 0, v249, vcc
	global_load_dwordx2 v[180:181], v[244:245], off
	s_nop 0
	global_load_dwordx2 v[248:249], v[248:249], off offset:128
	s_nop 0
	global_load_dwordx2 v[244:245], v[244:245], off offset:128
	s_waitcnt vmcnt(0)
	v_cvt_f32_ubyte1_e32 v211, v190
	v_cvt_f32_ubyte0_e32 v3, v192
	v_cvt_f32_ubyte1_e32 v153, v192
	v_cvt_f32_ubyte2_e32 v155, v192
	v_cvt_f32_ubyte3_e32 v157, v192
	v_cvt_f32_ubyte0_e32 v209, v193
	v_cvt_f32_ubyte1_e32 v197, v193
	v_cvt_f32_ubyte2_e32 v198, v193
	v_cvt_f32_ubyte3_e32 v199, v193
	v_rcp_iflag_f32_e32 v192, v3
	v_rcp_iflag_f32_e32 v193, v153
	v_rcp_iflag_f32_e32 v194, v155
	v_rcp_iflag_f32_e32 v195, v157
	v_rcp_iflag_f32_e32 v198, v198
	v_rcp_iflag_f32_e32 v199, v199
	v_rcp_iflag_f32_e32 v196, v209
	v_rcp_iflag_f32_e32 v197, v197
	v_cvt_f32_ubyte0_e32 v210, v190
	v_cvt_f32_ubyte3_e32 v201, v190
	v_cvt_f32_ubyte2_e32 v200, v190
	v_pk_mul_f32 v[192:193], v[192:193], v[210:211]
	v_pk_mul_f32 v[194:195], v[194:195], v[200:201]
	v_pk_mul_f32 v[106:107], v[106:107], v[192:193]
	v_cvt_f32_ubyte3_e32 v193, v191
	v_cvt_f32_ubyte2_e32 v192, v191
	v_pk_mul_f32 v[108:109], v[108:109], v[194:195]
	v_cvt_f32_ubyte1_e32 v195, v191
	v_cvt_f32_ubyte0_e32 v194, v191
	v_pk_mul_f32 v[192:193], v[198:199], v[192:193]
	v_cvt_f32_ubyte0_e32 v3, v238
	v_cvt_f32_ubyte1_e32 v153, v238
	v_pk_mul_f32 v[190:191], v[196:197], v[194:195]
	v_pk_mul_f32 v[116:117], v[116:117], v[192:193]
	v_cvt_f32_ubyte2_e32 v155, v238
	v_cvt_f32_ubyte3_e32 v157, v238
	v_cvt_f32_ubyte0_e32 v209, v239
	v_cvt_f32_ubyte1_e32 v193, v239
	v_cvt_f32_ubyte2_e32 v194, v239
	v_cvt_f32_ubyte3_e32 v195, v239
	v_rcp_iflag_f32_e32 v238, v3
	v_rcp_iflag_f32_e32 v239, v153
	v_pk_mul_f32 v[114:115], v[114:115], v[190:191]
	v_rcp_iflag_f32_e32 v190, v155
	v_rcp_iflag_f32_e32 v191, v157
	v_rcp_iflag_f32_e32 v194, v194
	v_rcp_iflag_f32_e32 v195, v195
	v_rcp_iflag_f32_e32 v192, v209
	v_rcp_iflag_f32_e32 v193, v193
	v_cvt_f32_ubyte1_e32 v199, v236
	v_cvt_f32_ubyte0_e32 v198, v236
	v_cvt_f32_ubyte3_e32 v197, v236
	v_cvt_f32_ubyte2_e32 v196, v236
	v_pk_mul_f32 v[238:239], v[238:239], v[198:199]
	v_pk_mul_f32 v[190:191], v[190:191], v[196:197]
	v_pk_mul_f32 v[126:127], v[126:127], v[238:239]
	v_cvt_f32_ubyte3_e32 v239, v237
	v_cvt_f32_ubyte2_e32 v238, v237
	v_pk_mul_f32 v[128:129], v[128:129], v[190:191]
	v_cvt_f32_ubyte1_e32 v191, v237
	v_cvt_f32_ubyte0_e32 v190, v237
	v_pk_mul_f32 v[238:239], v[194:195], v[238:239]
	v_cvt_f32_ubyte0_e32 v3, v188
	v_cvt_f32_ubyte1_e32 v153, v188
	v_pk_mul_f32 v[236:237], v[192:193], v[190:191]
	v_pk_mul_f32 v[132:133], v[132:133], v[238:239]
	v_cvt_f32_ubyte2_e32 v155, v188
	v_cvt_f32_ubyte3_e32 v157, v188
	v_cvt_f32_ubyte0_e32 v238, v189
	v_cvt_f32_ubyte1_e32 v239, v189
	v_cvt_f32_ubyte2_e32 v209, v189
	v_cvt_f32_ubyte3_e32 v191, v189
	v_rcp_iflag_f32_e32 v188, v3
	v_rcp_iflag_f32_e32 v189, v153
	v_pk_mul_f32 v[130:131], v[130:131], v[236:237]
	v_rcp_iflag_f32_e32 v236, v155
	v_rcp_iflag_f32_e32 v237, v157
	v_rcp_iflag_f32_e32 v190, v209
	v_rcp_iflag_f32_e32 v191, v191
	v_rcp_iflag_f32_e32 v238, v238
	v_rcp_iflag_f32_e32 v239, v239
	v_cvt_f32_ubyte1_e32 v195, v186
	v_cvt_f32_ubyte0_e32 v194, v186
	v_cvt_f32_ubyte3_e32 v193, v186
	v_cvt_f32_ubyte2_e32 v192, v186
	v_pk_mul_f32 v[188:189], v[188:189], v[194:195]
	v_pk_mul_f32 v[236:237], v[236:237], v[192:193]
	v_pk_mul_f32 v[102:103], v[102:103], v[188:189]
	v_cvt_f32_ubyte3_e32 v189, v187
	v_cvt_f32_ubyte2_e32 v188, v187
	v_pk_mul_f32 v[104:105], v[104:105], v[236:237]
	v_cvt_f32_ubyte1_e32 v237, v187
	v_cvt_f32_ubyte0_e32 v236, v187
	v_pk_mul_f32 v[188:189], v[190:191], v[188:189]
	v_cvt_f32_ubyte0_e32 v3, v242
	v_cvt_f32_ubyte1_e32 v153, v242
	v_pk_mul_f32 v[186:187], v[238:239], v[236:237]
	v_pk_mul_f32 v[112:113], v[112:113], v[188:189]
	v_cvt_f32_ubyte2_e32 v155, v242
	v_cvt_f32_ubyte3_e32 v157, v242
	v_cvt_f32_ubyte0_e32 v188, v243
	v_cvt_f32_ubyte1_e32 v189, v243
	v_cvt_f32_ubyte2_e32 v236, v243
	v_cvt_f32_ubyte3_e32 v237, v243
	v_rcp_iflag_f32_e32 v242, v3
	v_rcp_iflag_f32_e32 v243, v153
	v_pk_mul_f32 v[110:111], v[110:111], v[186:187]
	v_rcp_iflag_f32_e32 v186, v155
	v_rcp_iflag_f32_e32 v187, v157
	v_rcp_iflag_f32_e32 v236, v236
	v_rcp_iflag_f32_e32 v237, v237
	v_rcp_iflag_f32_e32 v188, v188
	v_rcp_iflag_f32_e32 v189, v189
	v_cvt_f32_ubyte1_e32 v191, v184
	v_cvt_f32_ubyte0_e32 v190, v184
	v_cvt_f32_ubyte3_e32 v239, v184
	v_cvt_f32_ubyte2_e32 v238, v184
	v_pk_mul_f32 v[242:243], v[242:243], v[190:191]
	v_pk_mul_f32 v[186:187], v[186:187], v[238:239]
	v_pk_mul_f32 v[122:123], v[122:123], v[242:243]
	v_cvt_f32_ubyte3_e32 v243, v185
	v_cvt_f32_ubyte2_e32 v242, v185
	v_pk_mul_f32 v[124:125], v[124:125], v[186:187]
	v_cvt_f32_ubyte1_e32 v187, v185
	v_cvt_f32_ubyte0_e32 v186, v185
	v_pk_mul_f32 v[242:243], v[236:237], v[242:243]
	v_cvt_f32_ubyte2_e32 v155, v240
	v_cvt_f32_ubyte3_e32 v157, v240
	v_pk_mul_f32 v[184:185], v[188:189], v[186:187]
	v_pk_mul_f32 v[120:121], v[120:121], v[242:243]
	v_cvt_f32_ubyte0_e32 v3, v240
	v_cvt_f32_ubyte1_e32 v153, v240
	v_cvt_f32_ubyte0_e32 v242, v241
	v_cvt_f32_ubyte1_e32 v243, v241
	v_cvt_f32_ubyte2_e32 v186, v241
	v_cvt_f32_ubyte3_e32 v187, v241
	v_rcp_iflag_f32_e32 v240, v155
	v_rcp_iflag_f32_e32 v241, v157
	v_pk_mul_f32 v[118:119], v[118:119], v[184:185]
	v_rcp_iflag_f32_e32 v184, v3
	v_rcp_iflag_f32_e32 v185, v153
	v_rcp_iflag_f32_e32 v242, v242
	v_rcp_iflag_f32_e32 v243, v243
	v_rcp_iflag_f32_e32 v186, v186
	v_rcp_iflag_f32_e32 v187, v187
	v_cvt_f32_ubyte3_e32 v189, v182
	v_cvt_f32_ubyte2_e32 v188, v182
	v_cvt_f32_ubyte1_e32 v237, v182
	v_cvt_f32_ubyte0_e32 v236, v182
	v_pk_mul_f32 v[240:241], v[240:241], v[188:189]
	v_pk_mul_f32 v[184:185], v[184:185], v[236:237]
	v_pk_mul_f32 v[92:93], v[92:93], v[240:241]
	v_cvt_f32_ubyte1_e32 v241, v183
	v_cvt_f32_ubyte0_e32 v240, v183
	v_pk_mul_f32 v[90:91], v[90:91], v[184:185]
	v_cvt_f32_ubyte3_e32 v185, v183
	v_cvt_f32_ubyte2_e32 v184, v183
	v_pk_mul_f32 v[182:183], v[242:243], v[240:241]
	v_cvt_f32_ubyte2_e32 v155, v246
	v_cvt_f32_ubyte3_e32 v157, v246
	v_pk_mul_f32 v[184:185], v[186:187], v[184:185]
	v_pk_mul_f32 v[86:87], v[86:87], v[182:183]
	v_cvt_f32_ubyte0_e32 v3, v246
	v_cvt_f32_ubyte1_e32 v153, v246
	v_rcp_iflag_f32_e32 v182, v155
	v_rcp_iflag_f32_e32 v183, v157
	v_pk_mul_f32 v[88:89], v[88:89], v[184:185]
	v_cvt_f32_ubyte0_e32 v184, v247
	v_cvt_f32_ubyte1_e32 v185, v247
	v_cvt_f32_ubyte2_e32 v240, v247
	v_cvt_f32_ubyte3_e32 v241, v247
	v_rcp_iflag_f32_e32 v246, v3
	v_rcp_iflag_f32_e32 v247, v153
	v_rcp_iflag_f32_e32 v184, v184
	v_rcp_iflag_f32_e32 v185, v185
	v_rcp_iflag_f32_e32 v240, v240
	v_rcp_iflag_f32_e32 v241, v241
	v_cvt_f32_ubyte3_e32 v243, v178
	v_cvt_f32_ubyte2_e32 v242, v178
	v_cvt_f32_ubyte1_e32 v187, v178
	v_cvt_f32_ubyte0_e32 v186, v178
	v_pk_mul_f32 v[182:183], v[182:183], v[242:243]
	v_pk_mul_f32 v[246:247], v[246:247], v[186:187]
	v_pk_mul_f32 v[100:101], v[100:101], v[182:183]
	v_cvt_f32_ubyte1_e32 v183, v179
	v_cvt_f32_ubyte0_e32 v182, v179
	v_pk_mul_f32 v[98:99], v[98:99], v[246:247]
	v_cvt_f32_ubyte3_e32 v247, v179
	v_cvt_f32_ubyte2_e32 v246, v179
	v_pk_mul_f32 v[178:179], v[184:185], v[182:183]
	v_cvt_f32_ubyte0_e32 v3, v180
	v_cvt_f32_ubyte1_e32 v153, v180
	v_pk_mul_f32 v[246:247], v[240:241], v[246:247]
	v_pk_mul_f32 v[94:95], v[94:95], v[178:179]
	v_cvt_f32_ubyte2_e32 v155, v180
	v_cvt_f32_ubyte3_e32 v157, v180
	v_rcp_iflag_f32_e32 v178, v3
	v_rcp_iflag_f32_e32 v179, v153
	v_pk_mul_f32 v[96:97], v[96:97], v[246:247]
	v_cvt_f32_ubyte0_e32 v246, v181
	v_cvt_f32_ubyte1_e32 v247, v181
	v_cvt_f32_ubyte2_e32 v182, v181
	v_cvt_f32_ubyte3_e32 v183, v181
	v_rcp_iflag_f32_e32 v180, v155
	v_rcp_iflag_f32_e32 v181, v157
	v_rcp_iflag_f32_e32 v182, v182
	v_rcp_iflag_f32_e32 v183, v183
	v_rcp_iflag_f32_e32 v246, v246
	v_rcp_iflag_f32_e32 v247, v247
	v_cvt_f32_ubyte1_e32 v241, v250
	v_cvt_f32_ubyte0_e32 v240, v250
	v_cvt_f32_ubyte3_e32 v185, v250
	v_cvt_f32_ubyte2_e32 v184, v250
	v_pk_mul_f32 v[178:179], v[178:179], v[240:241]
	v_pk_mul_f32 v[180:181], v[180:181], v[184:185]
	v_pk_mul_f32 v[74:75], v[74:75], v[178:179]
	v_cvt_f32_ubyte3_e32 v179, v251
	v_cvt_f32_ubyte2_e32 v178, v251
	v_pk_mul_f32 v[76:77], v[76:77], v[180:181]
	v_cvt_f32_ubyte1_e32 v181, v251
	v_cvt_f32_ubyte0_e32 v180, v251
	v_pk_mul_f32 v[178:179], v[182:183], v[178:179]
	v_cvt_f32_ubyte2_e32 v155, v244
	v_cvt_f32_ubyte3_e32 v157, v244
	v_pk_mul_f32 v[250:251], v[246:247], v[180:181]
	v_pk_mul_f32 v[72:73], v[72:73], v[178:179]
	v_cvt_f32_ubyte0_e32 v3, v244
	v_cvt_f32_ubyte1_e32 v153, v244
	v_rcp_iflag_f32_e32 v178, v155
	v_rcp_iflag_f32_e32 v179, v157
	v_pk_mul_f32 v[70:71], v[70:71], v[250:251]
	v_cvt_f32_ubyte0_e32 v180, v245
	v_cvt_f32_ubyte1_e32 v181, v245
	v_rcp_iflag_f32_e32 v250, v3
	v_rcp_iflag_f32_e32 v251, v153
	v_cvt_f32_ubyte2_e32 v244, v245
	v_cvt_f32_ubyte3_e32 v245, v245
	v_rcp_iflag_f32_e32 v180, v180
	v_rcp_iflag_f32_e32 v181, v181
	v_rcp_iflag_f32_e32 v244, v244
	v_rcp_iflag_f32_e32 v245, v245
	v_cvt_f32_ubyte3_e32 v247, v248
	v_cvt_f32_ubyte2_e32 v246, v248
	v_cvt_f32_ubyte1_e32 v183, v248
	v_cvt_f32_ubyte0_e32 v182, v248
	v_pk_mul_f32 v[178:179], v[178:179], v[246:247]
	v_pk_mul_f32 v[250:251], v[250:251], v[182:183]
	v_pk_mul_f32 v[84:85], v[84:85], v[178:179]
	v_cvt_f32_ubyte1_e32 v179, v249
	v_cvt_f32_ubyte0_e32 v178, v249
	v_pk_mul_f32 v[82:83], v[82:83], v[250:251]
	v_cvt_f32_ubyte3_e32 v251, v249
	v_cvt_f32_ubyte2_e32 v250, v249
	v_pk_mul_f32 v[248:249], v[180:181], v[178:179]
	v_pk_mul_f32 v[250:251], v[244:245], v[250:251]
	v_pk_mul_f32 v[78:79], v[78:79], v[248:249]
	v_lshl_add_u64 v[248:249], v[4:5], 0, v[166:167]
	v_pk_mul_f32 v[80:81], v[80:81], v[250:251]
	v_add_co_u32_e32 v250, vcc, s89, v248
	global_load_dwordx2 v[242:243], v[248:249], off
	s_nop 0
	v_addc_co_u32_e32 v251, vcc, 0, v249, vcc
	global_load_dwordx2 v[186:187], v[250:251], off
	global_load_dwordx2 v[182:183], v[248:249], off offset:128
	global_load_dwordx2 v[188:189], v[250:251], off offset:128
	v_lshl_add_u64 v[248:249], v[4:5], 0, v[168:169]
	v_add_co_u32_e32 v250, vcc, s89, v248
	global_load_dwordx2 v[236:237], v[248:249], off
	s_nop 0
	v_addc_co_u32_e32 v251, vcc, 0, v249, vcc
	global_load_dwordx2 v[238:239], v[250:251], off
	global_load_dwordx2 v[240:241], v[248:249], off offset:128
	global_load_dwordx2 v[190:191], v[250:251], off offset:128
	v_lshl_add_u64 v[248:249], v[4:5], 0, v[170:171]
	v_add_co_u32_e32 v250, vcc, s89, v248
	global_load_dwordx2 v[246:247], v[248:249], off
	s_nop 0
	v_addc_co_u32_e32 v251, vcc, 0, v249, vcc
	global_load_dwordx2 v[184:185], v[250:251], off
	global_load_dwordx2 v[180:181], v[248:249], off offset:128
	global_load_dwordx2 v[244:245], v[250:251], off offset:128
	v_lshl_add_u64 v[4:5], v[4:5], 0, v[172:173]
	v_add_co_u32_e32 v248, vcc, s89, v4
	global_load_dwordx2 v[250:251], v[4:5], off
	s_nop 0
	v_addc_co_u32_e32 v249, vcc, 0, v5, vcc
	global_load_dwordx2 v[178:179], v[248:249], off
	s_nop 0
	global_load_dwordx2 v[4:5], v[4:5], off offset:128
	s_nop 0
	global_load_dwordx2 v[248:249], v[248:249], off offset:128
	s_waitcnt vmcnt(15)
	v_cvt_f32_ubyte3_e32 v199, v242
	s_waitcnt vmcnt(14)
	v_cvt_f32_ubyte0_e32 v3, v186
	v_cvt_f32_ubyte1_e32 v153, v186
	v_cvt_f32_ubyte2_e32 v155, v186
	v_cvt_f32_ubyte3_e32 v157, v186
	v_cvt_f32_ubyte0_e32 v209, v187
	v_cvt_f32_ubyte1_e32 v195, v187
	v_cvt_f32_ubyte2_e32 v196, v187
	v_cvt_f32_ubyte3_e32 v197, v187
	v_rcp_iflag_f32_e32 v186, v3
	v_rcp_iflag_f32_e32 v187, v153
	v_rcp_iflag_f32_e32 v192, v155
	v_rcp_iflag_f32_e32 v193, v157
	v_rcp_iflag_f32_e32 v194, v209
	v_rcp_iflag_f32_e32 v195, v195
	v_rcp_iflag_f32_e32 v196, v196
	v_rcp_iflag_f32_e32 v197, v197
	v_cvt_f32_ubyte2_e32 v198, v242
	v_cvt_f32_ubyte1_e32 v201, v242
	v_cvt_f32_ubyte0_e32 v200, v242
	v_pk_mul_f32 v[186:187], v[186:187], v[200:201]
	v_pk_mul_f32 v[192:193], v[192:193], v[198:199]
	v_pk_mul_f32 v[66:67], v[66:67], v[186:187]
	v_pk_mul_f32 v[68:69], v[68:69], v[192:193]
	v_cvt_f32_ubyte3_e32 v187, v243
	v_cvt_f32_ubyte2_e32 v186, v243
	v_cvt_f32_ubyte1_e32 v193, v243
	v_cvt_f32_ubyte0_e32 v192, v243
	v_pk_mul_f32 v[242:243], v[194:195], v[192:193]
	v_pk_mul_f32 v[186:187], v[196:197], v[186:187]
	s_waitcnt vmcnt(12)
	v_cvt_f32_ubyte0_e32 v3, v188
	v_cvt_f32_ubyte1_e32 v153, v188
	v_cvt_f32_ubyte2_e32 v155, v188
	v_cvt_f32_ubyte3_e32 v157, v188
	v_pk_mul_f32 v[60:61], v[60:61], v[186:187]
	v_pk_mul_f32 v[58:59], v[58:59], v[242:243]
	v_rcp_iflag_f32_e32 v242, v3
	v_rcp_iflag_f32_e32 v243, v153
	v_rcp_iflag_f32_e32 v186, v155
	v_rcp_iflag_f32_e32 v187, v157
	v_cvt_f32_ubyte0_e32 v188, v189
	v_cvt_f32_ubyte1_e32 v209, v189
	v_cvt_f32_ubyte2_e32 v192, v189
	v_cvt_f32_ubyte3_e32 v193, v189
	v_rcp_iflag_f32_e32 v188, v188
	v_rcp_iflag_f32_e32 v189, v209
	v_rcp_iflag_f32_e32 v192, v192
	v_rcp_iflag_f32_e32 v193, v193
	v_cvt_f32_ubyte3_e32 v195, v182
	v_cvt_f32_ubyte2_e32 v194, v182
	v_cvt_f32_ubyte1_e32 v197, v182
	v_cvt_f32_ubyte0_e32 v196, v182
	v_pk_mul_f32 v[242:243], v[242:243], v[196:197]
	v_pk_mul_f32 v[186:187], v[186:187], v[194:195]
	v_pk_mul_f32 v[62:63], v[62:63], v[242:243]
	v_pk_mul_f32 v[64:65], v[64:65], v[186:187]
	v_cvt_f32_ubyte3_e32 v243, v183
	v_cvt_f32_ubyte2_e32 v242, v183
	v_cvt_f32_ubyte1_e32 v187, v183
	v_cvt_f32_ubyte0_e32 v186, v183
	v_pk_mul_f32 v[182:183], v[188:189], v[186:187]
	v_pk_mul_f32 v[242:243], v[192:193], v[242:243]
	s_waitcnt vmcnt(10)
	v_cvt_f32_ubyte0_e32 v3, v238
	v_cvt_f32_ubyte1_e32 v153, v238
	v_cvt_f32_ubyte2_e32 v155, v238
	v_cvt_f32_ubyte3_e32 v157, v238
	v_pk_mul_f32 v[56:57], v[56:57], v[242:243]
	v_pk_mul_f32 v[54:55], v[54:55], v[182:183]
	v_rcp_iflag_f32_e32 v182, v3
	v_rcp_iflag_f32_e32 v183, v153
	v_rcp_iflag_f32_e32 v242, v155
	v_rcp_iflag_f32_e32 v243, v157
	v_cvt_f32_ubyte0_e32 v186, v239
	v_cvt_f32_ubyte1_e32 v187, v239
	v_cvt_f32_ubyte2_e32 v188, v239
	v_cvt_f32_ubyte3_e32 v189, v239
	v_rcp_iflag_f32_e32 v186, v186
	v_rcp_iflag_f32_e32 v187, v187
	v_rcp_iflag_f32_e32 v188, v188
	v_rcp_iflag_f32_e32 v189, v189
	v_cvt_f32_ubyte3_e32 v239, v236
	v_cvt_f32_ubyte2_e32 v238, v236
	v_cvt_f32_ubyte1_e32 v193, v236
	v_cvt_f32_ubyte0_e32 v192, v236
	v_pk_mul_f32 v[182:183], v[182:183], v[192:193]
	v_pk_mul_f32 v[242:243], v[242:243], v[238:239]
	v_pk_mul_f32 v[50:51], v[50:51], v[182:183]
	v_pk_mul_f32 v[52:53], v[52:53], v[242:243]
	v_cvt_f32_ubyte3_e32 v183, v237
	v_cvt_f32_ubyte2_e32 v182, v237
	v_cvt_f32_ubyte1_e32 v243, v237
	v_cvt_f32_ubyte0_e32 v242, v237
	v_pk_mul_f32 v[242:243], v[186:187], v[242:243]
	v_pk_mul_f32 v[182:183], v[188:189], v[182:183]
	s_waitcnt vmcnt(8)
	v_cvt_f32_ubyte0_e32 v3, v190
	v_cvt_f32_ubyte1_e32 v153, v190
	v_cvt_f32_ubyte2_e32 v155, v190
	v_cvt_f32_ubyte3_e32 v157, v190
	v_pk_mul_f32 v[44:45], v[44:45], v[182:183]
	v_pk_mul_f32 v[42:43], v[42:43], v[242:243]
	v_rcp_iflag_f32_e32 v182, v3
	v_rcp_iflag_f32_e32 v183, v153
	v_rcp_iflag_f32_e32 v242, v155
	v_rcp_iflag_f32_e32 v243, v157
	v_cvt_f32_ubyte0_e32 v186, v191
	v_cvt_f32_ubyte1_e32 v187, v191
	v_cvt_f32_ubyte2_e32 v188, v191
	v_cvt_f32_ubyte3_e32 v189, v191
	v_rcp_iflag_f32_e32 v186, v186
	v_rcp_iflag_f32_e32 v187, v187
	v_rcp_iflag_f32_e32 v188, v188
	v_rcp_iflag_f32_e32 v189, v189
	v_cvt_f32_ubyte3_e32 v237, v240
	v_cvt_f32_ubyte2_e32 v236, v240
	v_cvt_f32_ubyte1_e32 v239, v240
	v_cvt_f32_ubyte0_e32 v238, v240
	v_pk_mul_f32 v[182:183], v[182:183], v[238:239]
	v_pk_mul_f32 v[242:243], v[242:243], v[236:237]
	v_pk_mul_f32 v[46:47], v[46:47], v[182:183]
	v_pk_mul_f32 v[48:49], v[48:49], v[242:243]
	v_cvt_f32_ubyte3_e32 v183, v241
	v_cvt_f32_ubyte2_e32 v182, v241
	v_cvt_f32_ubyte1_e32 v243, v241
	v_cvt_f32_ubyte0_e32 v242, v241
	v_pk_mul_f32 v[240:241], v[186:187], v[242:243]
	v_pk_mul_f32 v[182:183], v[188:189], v[182:183]
	s_waitcnt vmcnt(6)
	v_cvt_f32_ubyte0_e32 v3, v184
	v_cvt_f32_ubyte1_e32 v153, v184
	v_cvt_f32_ubyte2_e32 v155, v184
	v_cvt_f32_ubyte3_e32 v157, v184
	v_pk_mul_f32 v[40:41], v[40:41], v[182:183]
	v_pk_mul_f32 v[38:39], v[38:39], v[240:241]
	v_cvt_f32_ubyte0_e32 v240, v185
	v_cvt_f32_ubyte1_e32 v241, v185
	v_cvt_f32_ubyte2_e32 v242, v185
	v_cvt_f32_ubyte3_e32 v243, v185
	v_rcp_iflag_f32_e32 v182, v3
	v_rcp_iflag_f32_e32 v183, v153
	v_rcp_iflag_f32_e32 v184, v155
	v_rcp_iflag_f32_e32 v185, v157
	v_rcp_iflag_f32_e32 v240, v240
	v_rcp_iflag_f32_e32 v241, v241
	v_rcp_iflag_f32_e32 v242, v242
	v_rcp_iflag_f32_e32 v243, v243
	v_cvt_f32_ubyte3_e32 v187, v246
	v_cvt_f32_ubyte2_e32 v186, v246
	v_cvt_f32_ubyte1_e32 v189, v246
	v_cvt_f32_ubyte0_e32 v188, v246
	v_pk_mul_f32 v[182:183], v[182:183], v[188:189]
	v_pk_mul_f32 v[184:185], v[184:185], v[186:187]
	v_pk_mul_f32 v[34:35], v[34:35], v[182:183]
	v_pk_mul_f32 v[36:37], v[36:37], v[184:185]
	v_cvt_f32_ubyte3_e32 v183, v247
	v_cvt_f32_ubyte2_e32 v182, v247
	v_cvt_f32_ubyte1_e32 v185, v247
	v_cvt_f32_ubyte0_e32 v184, v247
	v_pk_mul_f32 v[246:247], v[240:241], v[184:185]
	v_pk_mul_f32 v[182:183], v[242:243], v[182:183]
	s_waitcnt vmcnt(4)
	v_cvt_f32_ubyte0_e32 v3, v244
	v_cvt_f32_ubyte1_e32 v153, v244
	v_cvt_f32_ubyte2_e32 v155, v244
	v_cvt_f32_ubyte3_e32 v157, v244
	v_pk_mul_f32 v[28:29], v[28:29], v[182:183]
	v_pk_mul_f32 v[26:27], v[26:27], v[246:247]
	v_cvt_f32_ubyte0_e32 v182, v245
	v_cvt_f32_ubyte1_e32 v183, v245
	v_cvt_f32_ubyte2_e32 v184, v245
	v_cvt_f32_ubyte3_e32 v185, v245
	v_rcp_iflag_f32_e32 v244, v3
	v_rcp_iflag_f32_e32 v245, v153
	v_rcp_iflag_f32_e32 v246, v155
	v_rcp_iflag_f32_e32 v247, v157
	v_rcp_iflag_f32_e32 v182, v182
	v_rcp_iflag_f32_e32 v183, v183
	v_rcp_iflag_f32_e32 v184, v184
	v_rcp_iflag_f32_e32 v185, v185
	v_cvt_f32_ubyte3_e32 v241, v180
	v_cvt_f32_ubyte2_e32 v240, v180
	v_cvt_f32_ubyte1_e32 v243, v180
	v_cvt_f32_ubyte0_e32 v242, v180
	v_pk_mul_f32 v[244:245], v[244:245], v[242:243]
	v_pk_mul_f32 v[246:247], v[246:247], v[240:241]
	v_pk_mul_f32 v[30:31], v[30:31], v[244:245]
	v_pk_mul_f32 v[32:33], v[32:33], v[246:247]
	v_cvt_f32_ubyte3_e32 v245, v181
	v_cvt_f32_ubyte2_e32 v244, v181
	v_cvt_f32_ubyte1_e32 v247, v181
	v_cvt_f32_ubyte0_e32 v246, v181
	v_pk_mul_f32 v[180:181], v[182:183], v[246:247]
	v_pk_mul_f32 v[244:245], v[184:185], v[244:245]
	s_waitcnt vmcnt(2)
	v_cvt_f32_ubyte0_e32 v3, v178
	v_cvt_f32_ubyte1_e32 v153, v178
	v_cvt_f32_ubyte2_e32 v155, v178
	v_cvt_f32_ubyte3_e32 v157, v178
	v_pk_mul_f32 v[24:25], v[24:25], v[244:245]
	v_pk_mul_f32 v[22:23], v[22:23], v[180:181]
	v_cvt_f32_ubyte0_e32 v244, v179
	v_cvt_f32_ubyte1_e32 v245, v179
	v_cvt_f32_ubyte2_e32 v246, v179
	v_cvt_f32_ubyte3_e32 v247, v179
	v_rcp_iflag_f32_e32 v178, v3
	v_rcp_iflag_f32_e32 v179, v153
	v_rcp_iflag_f32_e32 v180, v155
	v_rcp_iflag_f32_e32 v181, v157
	v_rcp_iflag_f32_e32 v244, v244
	v_rcp_iflag_f32_e32 v245, v245
	v_rcp_iflag_f32_e32 v246, v246
	v_rcp_iflag_f32_e32 v247, v247
	v_cvt_f32_ubyte3_e32 v183, v250
	v_cvt_f32_ubyte2_e32 v182, v250
	v_cvt_f32_ubyte1_e32 v185, v250
	v_cvt_f32_ubyte0_e32 v184, v250
	v_pk_mul_f32 v[178:179], v[178:179], v[184:185]
	v_pk_mul_f32 v[180:181], v[180:181], v[182:183]
	v_pk_mul_f32 v[18:19], v[18:19], v[178:179]
	v_pk_mul_f32 v[20:21], v[20:21], v[180:181]
	v_cvt_f32_ubyte3_e32 v179, v251
	v_cvt_f32_ubyte2_e32 v178, v251
	v_cvt_f32_ubyte1_e32 v181, v251
	v_cvt_f32_ubyte0_e32 v180, v251
	v_pk_mul_f32 v[250:251], v[244:245], v[180:181]
	v_pk_mul_f32 v[178:179], v[246:247], v[178:179]
	s_waitcnt vmcnt(0)
	v_cvt_f32_ubyte0_e32 v3, v248
	v_cvt_f32_ubyte1_e32 v153, v248
	v_cvt_f32_ubyte2_e32 v155, v248
	v_cvt_f32_ubyte3_e32 v157, v248
	v_pk_mul_f32 v[12:13], v[12:13], v[178:179]
	v_pk_mul_f32 v[10:11], v[10:11], v[250:251]
	v_cvt_f32_ubyte0_e32 v178, v249
	v_cvt_f32_ubyte1_e32 v179, v249
	v_cvt_f32_ubyte2_e32 v180, v249
	v_cvt_f32_ubyte3_e32 v181, v249
	v_rcp_iflag_f32_e32 v248, v3
	v_rcp_iflag_f32_e32 v249, v153
	v_rcp_iflag_f32_e32 v250, v155
	v_rcp_iflag_f32_e32 v251, v157
	v_rcp_iflag_f32_e32 v178, v178
	v_rcp_iflag_f32_e32 v179, v179
	v_rcp_iflag_f32_e32 v180, v180
	v_rcp_iflag_f32_e32 v181, v181
	v_cvt_f32_ubyte3_e32 v245, v4
	v_cvt_f32_ubyte2_e32 v244, v4
	v_cvt_f32_ubyte1_e32 v247, v4
	v_cvt_f32_ubyte0_e32 v246, v4
	v_pk_mul_f32 v[248:249], v[248:249], v[246:247]
	v_pk_mul_f32 v[250:251], v[250:251], v[244:245]
	v_pk_mul_f32 v[14:15], v[14:15], v[248:249]
	v_pk_mul_f32 v[16:17], v[16:17], v[250:251]
	v_cvt_f32_ubyte3_e32 v249, v5
	v_cvt_f32_ubyte2_e32 v248, v5
	v_cvt_f32_ubyte1_e32 v251, v5
	v_cvt_f32_ubyte0_e32 v250, v5
	v_pk_mul_f32 v[4:5], v[178:179], v[250:251]
	v_pk_mul_f32 v[248:249], v[180:181], v[248:249]
	v_pk_mul_f32 v[6:7], v[6:7], v[4:5]
	v_pk_mul_f32 v[8:9], v[8:9], v[248:249]
.LBB0_1285:
	v_add_u32_e32 v3, s90, v206
	ds_read_b128 v[248:251], v3
	ds_read_b128 v[178:181], v3 offset:1024
	ds_read_b128 v[244:247], v3 offset:2048
	ds_read_b128 v[182:185], v3 offset:3072
	v_add_u32_e32 v3, s91, v206
	ds_read_b128 v[240:243], v3
	ds_read_b128 v[186:189], v3 offset:1024
	ds_read_b128 v[236:239], v3 offset:2048
	ds_read_b128 v[190:193], v3 offset:3072
	s_add_i32 s14, s58, 2
	s_add_u32 s59, s56, 0xfff00080
	s_addc_u32 s60, s57, -1
	s_cmp_eq_u32 s92, s58
	s_cselect_b32 s61, s1, s60
	s_cselect_b32 s60, s45, s59
	s_cselect_b32 s59, s47, s82
	s_cselect_b32 s58, s49, s93
	v_lshl_add_u64 v[4:5], s[56:57], 0, v[148:149]
	s_add_i32 m0, s55, 0xc000
	ds_read_b128 v[194:197], v208
	ds_read_b128 v[198:201], v208 offset:1024
	ds_read_b128 v[210:213], v208 offset:2048
	ds_read_b128 v[214:217], v208 offset:3072
	ds_read_b128 v[218:221], v208 offset:4096
	ds_read_b128 v[222:225], v208 offset:5120
	ds_read_b128 v[226:229], v208 offset:6144
	ds_read_b128 v[230:233], v208 offset:7168
	global_load_lds_dwordx4 v[4:5], off
	v_lshl_add_u64 v[4:5], s[56:57], 0, v[150:151]
	s_add_i32 m0, s55, 0xe000
	s_nop 0
	global_load_lds_dwordx4 v[4:5], off
	s_waitcnt vmcnt(8)
	s_waitcnt lgkmcnt(0)
	s_barrier
	s_setprio 1
	s_waitcnt lgkmcnt(0)
	v_mfma_f32_16x16x32_bf16 v[106:109], v[248:251], v[194:197], v[106:109]
	v_mfma_f32_16x16x32_bf16 v[106:109], v[178:181], v[198:201], v[106:109]
	v_mfma_f32_16x16x32_bf16 v[114:117], v[244:247], v[194:197], v[114:117]
	v_mfma_f32_16x16x32_bf16 v[114:117], v[182:185], v[198:201], v[114:117]
	v_mfma_f32_16x16x32_bf16 v[110:113], v[244:247], v[210:213], v[110:113]
	v_mfma_f32_16x16x32_bf16 v[110:113], v[182:185], v[214:217], v[110:113]
	v_mfma_f32_16x16x32_bf16 v[102:105], v[248:251], v[210:213], v[102:105]
	v_mfma_f32_16x16x32_bf16 v[102:105], v[178:181], v[214:217], v[102:105]
	v_mfma_f32_16x16x32_bf16 v[90:93], v[248:251], v[218:221], v[90:93]
	v_mfma_f32_16x16x32_bf16 v[90:93], v[178:181], v[222:225], v[90:93]
	v_mfma_f32_16x16x32_bf16 v[86:89], v[244:247], v[218:221], v[86:89]
	v_mfma_f32_16x16x32_bf16 v[86:89], v[182:185], v[222:225], v[86:89]
	v_mfma_f32_16x16x32_bf16 v[70:73], v[244:247], v[226:229], v[70:73]
	v_mfma_f32_16x16x32_bf16 v[70:73], v[182:185], v[230:233], v[70:73]
	v_mfma_f32_16x16x32_bf16 v[74:77], v[248:251], v[226:229], v[74:77]
	v_mfma_f32_16x16x32_bf16 v[74:77], v[178:181], v[230:233], v[74:77]
	s_setprio 0
	s_setprio 1
	v_mfma_f32_16x16x32_bf16 v[126:129], v[240:243], v[194:197], v[126:129]
	v_mfma_f32_16x16x32_bf16 v[126:129], v[186:189], v[198:201], v[126:129]
	v_mfma_f32_16x16x32_bf16 v[130:133], v[236:239], v[194:197], v[130:133]
	v_mfma_f32_16x16x32_bf16 v[130:133], v[190:193], v[198:201], v[130:133]
	v_mfma_f32_16x16x32_bf16 v[118:121], v[236:239], v[210:213], v[118:121]
	v_mfma_f32_16x16x32_bf16 v[118:121], v[190:193], v[214:217], v[118:121]
	v_mfma_f32_16x16x32_bf16 v[122:125], v[240:243], v[210:213], v[122:125]
	v_mfma_f32_16x16x32_bf16 v[122:125], v[186:189], v[214:217], v[122:125]
	v_mfma_f32_16x16x32_bf16 v[98:101], v[240:243], v[218:221], v[98:101]
	v_mfma_f32_16x16x32_bf16 v[98:101], v[186:189], v[222:225], v[98:101]
	v_mfma_f32_16x16x32_bf16 v[94:97], v[236:239], v[218:221], v[94:97]
	v_mfma_f32_16x16x32_bf16 v[94:97], v[190:193], v[222:225], v[94:97]
	v_mfma_f32_16x16x32_bf16 v[78:81], v[236:239], v[226:229], v[78:81]
	v_mfma_f32_16x16x32_bf16 v[78:81], v[190:193], v[230:233], v[78:81]
	v_mfma_f32_16x16x32_bf16 v[82:85], v[240:243], v[226:229], v[82:85]
	v_mfma_f32_16x16x32_bf16 v[82:85], v[186:189], v[230:233], v[82:85]
	s_setprio 0
	s_barrier
	s_add_i32 vcc_lo, s90, s66
	v_lshl_add_u64 v[176:177], s[58:59], 0, v[140:141]
	s_mov_b32 m0, vcc_lo
	ds_read_b128 v[194:197], v208 offset:16384
	ds_read_b128 v[198:201], v208 offset:17408
	ds_read_b128 v[210:213], v208 offset:18432
	ds_read_b128 v[214:217], v208 offset:19456
	ds_read_b128 v[218:221], v208 offset:20480
	ds_read_b128 v[222:225], v208 offset:21504
	ds_read_b128 v[226:229], v208 offset:22528
	ds_read_b128 v[230:233], v208 offset:23552
	global_load_lds_dwordx4 v[176:177], off
	s_add_i32 m0, vcc_lo, 0x2000
	s_add_u32 vcc_lo, s58, 0x100000
	v_lshl_add_u64 v[202:203], s[58:59], 0, v[144:145]
	s_addc_u32 vcc_hi, s59, 0
	s_add_i32 s83, s91, s66
	global_load_lds_dwordx4 v[202:203], off
	v_lshl_add_u64 v[4:5], vcc, 0, v[140:141]
	s_mov_b32 m0, s83
	v_lshl_add_u64 v[234:235], s[60:61], 0, v[136:137]
	global_load_lds_dwordx4 v[4:5], off
	v_lshl_add_u64 v[4:5], vcc, 0, v[144:145]
	s_add_i32 m0, s83, 0x2000
	v_lshl_add_u64 v[252:253], s[60:61], 0, v[142:143]
	global_load_lds_dwordx4 v[4:5], off
	s_mov_b32 m0, s55
	s_nop 0
	global_load_lds_dwordx4 v[234:235], off
	s_mov_b32 m0, s72
	s_nop 0
	global_load_lds_dwordx4 v[252:253], off
	s_waitcnt vmcnt(8)
	s_waitcnt lgkmcnt(0)
	s_barrier
	s_setprio 1
	s_waitcnt lgkmcnt(0)
	v_mfma_f32_16x16x32_bf16 v[66:69], v[248:251], v[194:197], v[66:69]
	v_mfma_f32_16x16x32_bf16 v[66:69], v[178:181], v[198:201], v[66:69]
	v_mfma_f32_16x16x32_bf16 v[58:61], v[244:247], v[194:197], v[58:61]
	v_mfma_f32_16x16x32_bf16 v[58:61], v[182:185], v[198:201], v[58:61]
	v_mfma_f32_16x16x32_bf16 v[42:45], v[244:247], v[210:213], v[42:45]
	v_mfma_f32_16x16x32_bf16 v[42:45], v[182:185], v[214:217], v[42:45]
	v_mfma_f32_16x16x32_bf16 v[50:53], v[248:251], v[210:213], v[50:53]
	v_mfma_f32_16x16x32_bf16 v[50:53], v[178:181], v[214:217], v[50:53]
	v_mfma_f32_16x16x32_bf16 v[34:37], v[248:251], v[218:221], v[34:37]
	v_mfma_f32_16x16x32_bf16 v[34:37], v[178:181], v[222:225], v[34:37]
	v_mfma_f32_16x16x32_bf16 v[26:29], v[244:247], v[218:221], v[26:29]
	v_mfma_f32_16x16x32_bf16 v[26:29], v[182:185], v[222:225], v[26:29]
	v_mfma_f32_16x16x32_bf16 v[10:13], v[244:247], v[226:229], v[10:13]
	v_mfma_f32_16x16x32_bf16 v[10:13], v[182:185], v[230:233], v[10:13]
	v_mfma_f32_16x16x32_bf16 v[18:21], v[248:251], v[226:229], v[18:21]
	v_mfma_f32_16x16x32_bf16 v[18:21], v[178:181], v[230:233], v[18:21]
	s_setprio 0
	s_setprio 1
	v_mfma_f32_16x16x32_bf16 v[62:65], v[240:243], v[194:197], v[62:65]
	v_mfma_f32_16x16x32_bf16 v[62:65], v[186:189], v[198:201], v[62:65]
	v_mfma_f32_16x16x32_bf16 v[54:57], v[236:239], v[194:197], v[54:57]
	v_mfma_f32_16x16x32_bf16 v[54:57], v[190:193], v[198:201], v[54:57]
	v_mfma_f32_16x16x32_bf16 v[38:41], v[236:239], v[210:213], v[38:41]
	v_mfma_f32_16x16x32_bf16 v[38:41], v[190:193], v[214:217], v[38:41]
	v_mfma_f32_16x16x32_bf16 v[46:49], v[240:243], v[210:213], v[46:49]
	v_mfma_f32_16x16x32_bf16 v[46:49], v[186:189], v[214:217], v[46:49]
	v_mfma_f32_16x16x32_bf16 v[30:33], v[240:243], v[218:221], v[30:33]
	v_mfma_f32_16x16x32_bf16 v[30:33], v[186:189], v[222:225], v[30:33]
	v_mfma_f32_16x16x32_bf16 v[22:25], v[236:239], v[218:221], v[22:25]
	v_mfma_f32_16x16x32_bf16 v[22:25], v[190:193], v[222:225], v[22:25]
	v_mfma_f32_16x16x32_bf16 v[4:7], v[236:239], v[226:229], v[6:9]
	v_mfma_f32_16x16x32_bf16 v[4:7], v[190:193], v[230:233], v[4:7]
	v_mfma_f32_16x16x32_bf16 v[14:17], v[240:243], v[226:229], v[14:17]
	v_mfma_f32_16x16x32_bf16 v[14:17], v[186:189], v[230:233], v[14:17]
	s_setprio 0
	s_barrier
	s_add_i32 s83, 0, 0x18000
	v_add_u32_e32 v3, s83, v206
	s_add_i32 vcc_lo, 0, 0x1c000
	ds_read_b128 v[248:251], v3
	ds_read_b128 v[178:181], v3 offset:1024
	ds_read_b128 v[244:247], v3 offset:2048
	ds_read_b128 v[182:185], v3 offset:3072
	v_add_u32_e32 v3, vcc_lo, v206
	ds_read_b128 v[240:243], v3
	ds_read_b128 v[186:189], v3 offset:1024
	ds_read_b128 v[236:239], v3 offset:2048
	ds_read_b128 v[190:193], v3 offset:3072
	s_add_u32 s60, s60, 0x100000
	s_addc_u32 s61, s61, 0
	s_mov_b32 m0, s73
	v_lshl_add_u64 v[8:9], s[60:61], 0, v[136:137]
	ds_read_b128 v[194:197], v208 offset:32768
	ds_read_b128 v[198:201], v208 offset:33792
	ds_read_b128 v[210:213], v208 offset:34816
	ds_read_b128 v[214:217], v208 offset:35840
	ds_read_b128 v[218:221], v208 offset:36864
	ds_read_b128 v[222:225], v208 offset:37888
	ds_read_b128 v[226:229], v208 offset:38912
	ds_read_b128 v[230:233], v208 offset:39936
	global_load_lds_dwordx4 v[8:9], off
	v_lshl_add_u64 v[8:9], s[60:61], 0, v[142:143]
	s_mov_b32 m0, s74
	s_nop 0
	global_load_lds_dwordx4 v[8:9], off
	s_waitcnt vmcnt(8)
	s_waitcnt lgkmcnt(0)
	s_barrier
	s_setprio 1
	s_waitcnt lgkmcnt(0)
	v_mfma_f32_16x16x32_bf16 v[106:109], v[248:251], v[194:197], v[106:109]
	v_mfma_f32_16x16x32_bf16 v[106:109], v[178:181], v[198:201], v[106:109]
	v_mfma_f32_16x16x32_bf16 v[114:117], v[244:247], v[194:197], v[114:117]
	v_mfma_f32_16x16x32_bf16 v[114:117], v[182:185], v[198:201], v[114:117]
	v_mfma_f32_16x16x32_bf16 v[110:113], v[244:247], v[210:213], v[110:113]
	v_mfma_f32_16x16x32_bf16 v[110:113], v[182:185], v[214:217], v[110:113]
	v_mfma_f32_16x16x32_bf16 v[102:105], v[248:251], v[210:213], v[102:105]
	v_mfma_f32_16x16x32_bf16 v[102:105], v[178:181], v[214:217], v[102:105]
	v_mfma_f32_16x16x32_bf16 v[90:93], v[248:251], v[218:221], v[90:93]
	v_mfma_f32_16x16x32_bf16 v[90:93], v[178:181], v[222:225], v[90:93]
	v_mfma_f32_16x16x32_bf16 v[86:89], v[244:247], v[218:221], v[86:89]
	v_mfma_f32_16x16x32_bf16 v[86:89], v[182:185], v[222:225], v[86:89]
	v_mfma_f32_16x16x32_bf16 v[70:73], v[244:247], v[226:229], v[70:73]
	v_mfma_f32_16x16x32_bf16 v[70:73], v[182:185], v[230:233], v[70:73]
	v_mfma_f32_16x16x32_bf16 v[74:77], v[248:251], v[226:229], v[74:77]
	v_mfma_f32_16x16x32_bf16 v[74:77], v[178:181], v[230:233], v[74:77]
	s_setprio 0
	s_setprio 1
	v_mfma_f32_16x16x32_bf16 v[126:129], v[240:243], v[194:197], v[126:129]
	v_mfma_f32_16x16x32_bf16 v[126:129], v[186:189], v[198:201], v[126:129]
	v_mfma_f32_16x16x32_bf16 v[130:133], v[236:239], v[194:197], v[130:133]
	v_mfma_f32_16x16x32_bf16 v[130:133], v[190:193], v[198:201], v[130:133]
	v_mfma_f32_16x16x32_bf16 v[118:121], v[236:239], v[210:213], v[118:121]
	v_mfma_f32_16x16x32_bf16 v[118:121], v[190:193], v[214:217], v[118:121]
	v_mfma_f32_16x16x32_bf16 v[122:125], v[240:243], v[210:213], v[122:125]
	v_mfma_f32_16x16x32_bf16 v[122:125], v[186:189], v[214:217], v[122:125]
	v_mfma_f32_16x16x32_bf16 v[98:101], v[240:243], v[218:221], v[98:101]
	v_mfma_f32_16x16x32_bf16 v[98:101], v[186:189], v[222:225], v[98:101]
	v_mfma_f32_16x16x32_bf16 v[94:97], v[236:239], v[218:221], v[94:97]
	v_mfma_f32_16x16x32_bf16 v[94:97], v[190:193], v[222:225], v[94:97]
	v_mfma_f32_16x16x32_bf16 v[78:81], v[236:239], v[226:229], v[78:81]
	v_mfma_f32_16x16x32_bf16 v[78:81], v[190:193], v[230:233], v[78:81]
	v_mfma_f32_16x16x32_bf16 v[82:85], v[240:243], v[226:229], v[82:85]
	v_mfma_f32_16x16x32_bf16 v[82:85], v[186:189], v[230:233], v[82:85]
	s_setprio 0
	s_barrier
	s_add_i32 s60, s83, s66
	v_lshl_add_u64 v[8:9], v[176:177], 0, s[20:21]
	s_mov_b32 m0, s60
	ds_read_b128 v[194:197], v208 offset:49152
	ds_read_b128 v[198:201], v208 offset:50176
	ds_read_b128 v[210:213], v208 offset:51200
	ds_read_b128 v[214:217], v208 offset:52224
	ds_read_b128 v[218:221], v208 offset:53248
	ds_read_b128 v[222:225], v208 offset:54272
	ds_read_b128 v[226:229], v208 offset:55296
	ds_read_b128 v[230:233], v208 offset:56320
	global_load_lds_dwordx4 v[8:9], off
	s_add_i32 m0, s60, 0x2000
	s_add_u32 s58, s58, 0x100080
	v_lshl_add_u64 v[8:9], v[202:203], 0, s[20:21]
	s_addc_u32 s59, s59, 0
	s_add_i32 s60, vcc_lo, s66
	global_load_lds_dwordx4 v[8:9], off
	v_lshl_add_u64 v[8:9], s[58:59], 0, v[140:141]
	s_mov_b32 m0, s60
	s_nop 0
	global_load_lds_dwordx4 v[8:9], off
	v_lshl_add_u64 v[8:9], s[58:59], 0, v[144:145]
	s_add_i32 m0, s60, 0x2000
	s_nop 0
	global_load_lds_dwordx4 v[8:9], off
	v_lshl_add_u64 v[8:9], v[234:235], 0, s[20:21]
	s_mov_b32 m0, s76
	s_nop 0
	global_load_lds_dwordx4 v[8:9], off
	v_lshl_add_u64 v[8:9], v[252:253], 0, s[20:21]
	s_mov_b32 m0, s77
	s_nop 0
	global_load_lds_dwordx4 v[8:9], off
	s_waitcnt vmcnt(8)
	s_waitcnt lgkmcnt(0)
	s_barrier
	s_setprio 1
	s_waitcnt lgkmcnt(0)
	v_mfma_f32_16x16x32_bf16 v[66:69], v[248:251], v[194:197], v[66:69]
	v_mfma_f32_16x16x32_bf16 v[66:69], v[178:181], v[198:201], v[66:69]
	v_mfma_f32_16x16x32_bf16 v[58:61], v[244:247], v[194:197], v[58:61]
	v_mfma_f32_16x16x32_bf16 v[58:61], v[182:185], v[198:201], v[58:61]
	v_mfma_f32_16x16x32_bf16 v[42:45], v[244:247], v[210:213], v[42:45]
	v_mfma_f32_16x16x32_bf16 v[42:45], v[182:185], v[214:217], v[42:45]
	v_mfma_f32_16x16x32_bf16 v[50:53], v[248:251], v[210:213], v[50:53]
	v_mfma_f32_16x16x32_bf16 v[50:53], v[178:181], v[214:217], v[50:53]
	v_mfma_f32_16x16x32_bf16 v[34:37], v[248:251], v[218:221], v[34:37]
	v_mfma_f32_16x16x32_bf16 v[34:37], v[178:181], v[222:225], v[34:37]
	v_mfma_f32_16x16x32_bf16 v[26:29], v[244:247], v[218:221], v[26:29]
	v_mfma_f32_16x16x32_bf16 v[26:29], v[182:185], v[222:225], v[26:29]
	v_mfma_f32_16x16x32_bf16 v[8:11], v[244:247], v[226:229], v[10:13]
	v_mfma_f32_16x16x32_bf16 v[10:13], v[182:185], v[230:233], v[8:11]
	v_mfma_f32_16x16x32_bf16 v[18:21], v[248:251], v[226:229], v[18:21]
	v_mfma_f32_16x16x32_bf16 v[18:21], v[178:181], v[230:233], v[18:21]
	s_setprio 0
	s_setprio 1
	v_mfma_f32_16x16x32_bf16 v[62:65], v[240:243], v[194:197], v[62:65]
	v_mfma_f32_16x16x32_bf16 v[62:65], v[186:189], v[198:201], v[62:65]
	v_mfma_f32_16x16x32_bf16 v[54:57], v[236:239], v[194:197], v[54:57]
	v_mfma_f32_16x16x32_bf16 v[54:57], v[190:193], v[198:201], v[54:57]
	v_mfma_f32_16x16x32_bf16 v[38:41], v[236:239], v[210:213], v[38:41]
	v_mfma_f32_16x16x32_bf16 v[38:41], v[190:193], v[214:217], v[38:41]
	v_mfma_f32_16x16x32_bf16 v[46:49], v[240:243], v[210:213], v[46:49]
	v_mfma_f32_16x16x32_bf16 v[46:49], v[186:189], v[214:217], v[46:49]
	v_mfma_f32_16x16x32_bf16 v[30:33], v[240:243], v[218:221], v[30:33]
	v_mfma_f32_16x16x32_bf16 v[30:33], v[186:189], v[222:225], v[30:33]
	v_mfma_f32_16x16x32_bf16 v[22:25], v[236:239], v[218:221], v[22:25]
	v_mfma_f32_16x16x32_bf16 v[22:25], v[190:193], v[222:225], v[22:25]
	v_mfma_f32_16x16x32_bf16 v[4:7], v[236:239], v[226:229], v[4:7]
	v_mfma_f32_16x16x32_bf16 v[6:9], v[190:193], v[230:233], v[4:7]
	v_mfma_f32_16x16x32_bf16 v[14:17], v[240:243], v[226:229], v[14:17]
	v_mfma_f32_16x16x32_bf16 v[14:17], v[186:189], v[230:233], v[14:17]
	s_setprio 0
	s_barrier
	s_add_u32 s56, s56, 0x100
	s_addc_u32 s57, s57, 0
	s_add_u32 s93, s93, 0x100
	s_addc_u32 s82, s82, 0
	s_cmp_ge_i32 s14, s39
	s_cbranch_scc1 .LBB0_1288
	s_mov_b32 s58, s14
	s_branch .LBB0_1283
